# GEMM1 K-loop: s_setprio flips removed (A/B of the priority hypothesis), lean epilogue kept
# baseline (speedup 1.0000x reference)
; #define PG8_STAGE(bufoff, gbase, voff) do { _Pragma("unroll") for (int _i = 0; _i < 2; ++_i) \
;         __builtin_amdgcn_global_load_lds((const unsigned*)((const char*)(gbase) + (voff)[_i]), (PG8_LAS unsigned*)(lds + (bufoff) + ldsw + _i * 8192), 16, 0, 0); } while (0)
; #define PG8_LDA(dst, b, h) do { _Pragma("unroll") for (int m = 0; m < 4; ++m) _Pragma("unroll") for (int k = 0; k < 2; ++k) dst[m][k] = *(const PG8_LAS bf16x8*)(lds + PG8_SA(b, h) + aoff + m * 2048 + k * 1024); } while (0)
; #define PG8_LDB(dst, b, h) do { _Pragma("unroll") for (int n = 0; n < 2; ++n) _Pragma("unroll") for (int k = 0; k < 2; ++k) dst[n][k] = *(const PG8_LAS bf16x8*)(lds + PG8_SB(b, h) + boff + n * 2048 + k * 1024); } while (0)
; #define PG8_WAIT_V(n) asm volatile("s_waitcnt vmcnt(" #n ")" ::: "memory")
; #define PG8_WAIT_L(n) asm volatile("s_waitcnt lgkmcnt(" #n ")" ::: "memory")
; #define PG8_BAR __builtin_amdgcn_s_barrier()
; #define PG8_SCHED __builtin_amdgcn_sched_barrier(0)
; template <class Epi, class Sched, bool ALIGN_EPI = false, bool SP2 = false>
; __device__ __forceinline__ void gemm_phase(PG8_LAS unsigned char* lds, const Gemm g, const Sched& S, const Epi& E) {
;     ...
;         for (int t = 0; t < nt; t += 2) {
;             const bool last = (t == nt - 2);
;             const char* a1 = cA + (size_t)(t + 1) * kstep;
;             const char* a2 = last ? nA : cA + (size_t)(t + 2) * kstep; const char* b2 = last ? nB : cB + (size_t)(t + 2) * kstep;
;             const char* a3 = a2 + kstep; const char* b3 = b2 + kstep;
;             if (last && has_next) S.a_ready(nxt);
;             if constexpr (SP2) {
;             PG8_LDB(B0, 0, 0); PG8_LDB(B1, 0, 1); PG8_SCHED; PG8_LDA(At, 0, 0); PG8_STAGE(PG8_SA(1, 1), a1 + hstep, voffA);
;             PG8_WAIT_V(8); PG8_WAIT_L(0); PG8_BAR; PG8_MMA(0, 0, At, B0); PG8_MMA(0, 1, At, B1); PG8_BAR; PG8_SCHED;
;             PG8_LDA(At, 0, 1); PG8_STAGE(PG8_SB(0, 0), b2, voffB); PG8_STAGE(PG8_SB(0, 1), b2 + hstep, voffB); PG8_STAGE(PG8_SA(0, 0), a2, voffA);
;             PG8_WAIT_V(8); PG8_WAIT_L(0); PG8_BAR; PG8_MMA(1, 0, At, B0); PG8_MMA(1, 1, At, B1); PG8_BAR; PG8_SCHED;
.LBB0_153:
	s_add_u32 s28, s26, 0xfffc0080
	s_addc_u32 s29, s27, -1
	s_add_i32 s54, 0, 0x10000
	s_cmp_eq_u32 s45, 12
	s_cselect_b32 s31, s1, s29
	s_cselect_b32 s30, s25, s28
	v_add_u32_e32 v0, s54, v160
	s_cselect_b32 s29, s23, s43
	s_cselect_b32 s28, s41, s42
	s_add_i32 s56, 0, 0x14000
	ds_read_b128 v[142:145], v0
	ds_read_b128 v[146:149], v0 offset:1024
	ds_read_b128 v[150:153], v0 offset:2048
	ds_read_b128 v[154:157], v0 offset:3072
	v_add_u32_e32 v0, s56, v160
	ds_read_b128 v[184:187], v0
	ds_read_b128 v[188:191], v0 offset:1024
	ds_read_b128 v[192:195], v0 offset:2048
	ds_read_b128 v[196:199], v0 offset:3072
	v_lshl_add_u64 v[244:245], s[26:27], 0, v[138:139]
	s_add_i32 m0, s93, 0xc000
	ds_read_b128 v[200:203], v182
	ds_read_b128 v[204:207], v182 offset:1024
	ds_read_b128 v[208:211], v182 offset:2048
	ds_read_b128 v[212:215], v182 offset:3072
	ds_read_b128 v[216:219], v182 offset:4096
	ds_read_b128 v[220:223], v182 offset:5120
	ds_read_b128 v[236:239], v182 offset:6144
	ds_read_b128 v[240:243], v182 offset:7168
	global_load_lds_dwordx4 v[244:245], off
	v_lshl_add_u64 v[244:245], s[26:27], 0, v[140:141]
	s_add_i32 m0, s93, 0xe000
	s_nop 0
	global_load_lds_dwordx4 v[244:245], off
	s_waitcnt vmcnt(8)
	s_waitcnt lgkmcnt(0)
	s_barrier
	s_waitcnt lgkmcnt(0)
	v_mfma_f32_16x16x32_f16 v[126:129], v[142:145], v[200:203], v[126:129]
	v_mfma_f32_16x16x32_f16 v[122:125], v[150:153], v[200:203], v[122:125]
	v_mfma_f32_16x16x32_f16 v[110:113], v[142:145], v[208:211], v[110:113]
	v_mfma_f32_16x16x32_f16 v[106:109], v[150:153], v[208:211], v[106:109]
	v_mfma_f32_16x16x32_f16 v[94:97], v[142:145], v[216:219], v[94:97]
	v_mfma_f32_16x16x32_f16 v[90:93], v[150:153], v[216:219], v[90:93]
	v_mfma_f32_16x16x32_f16 v[78:81], v[142:145], v[236:239], v[78:81]
	v_mfma_f32_16x16x32_f16 v[74:77], v[150:153], v[236:239], v[74:77]
	v_mfma_f32_16x16x32_f16 v[126:129], v[146:149], v[204:207], v[126:129]
	v_mfma_f32_16x16x32_f16 v[122:125], v[154:157], v[204:207], v[122:125]
	v_mfma_f32_16x16x32_f16 v[110:113], v[146:149], v[212:215], v[110:113]
	v_mfma_f32_16x16x32_f16 v[106:109], v[154:157], v[212:215], v[106:109]
	v_mfma_f32_16x16x32_f16 v[94:97], v[146:149], v[220:223], v[94:97]
	v_mfma_f32_16x16x32_f16 v[90:93], v[154:157], v[220:223], v[90:93]
	v_mfma_f32_16x16x32_f16 v[78:81], v[146:149], v[240:243], v[78:81]
	v_mfma_f32_16x16x32_f16 v[74:77], v[154:157], v[240:243], v[74:77]
	v_mfma_f32_16x16x32_f16 v[118:121], v[184:187], v[200:203], v[118:121]
	v_mfma_f32_16x16x32_f16 v[114:117], v[192:195], v[200:203], v[114:117]
	v_mfma_f32_16x16x32_f16 v[102:105], v[184:187], v[208:211], v[102:105]
	v_mfma_f32_16x16x32_f16 v[98:101], v[192:195], v[208:211], v[98:101]
	v_mfma_f32_16x16x32_f16 v[86:89], v[184:187], v[216:219], v[86:89]
	v_mfma_f32_16x16x32_f16 v[82:85], v[192:195], v[216:219], v[82:85]
	v_mfma_f32_16x16x32_f16 v[70:73], v[184:187], v[236:239], v[70:73]
	v_mfma_f32_16x16x32_f16 v[66:69], v[192:195], v[236:239], v[66:69]
	v_mfma_f32_16x16x32_f16 v[118:121], v[188:191], v[204:207], v[118:121]
	v_mfma_f32_16x16x32_f16 v[114:117], v[196:199], v[204:207], v[114:117]
	v_mfma_f32_16x16x32_f16 v[102:105], v[188:191], v[212:215], v[102:105]
	v_mfma_f32_16x16x32_f16 v[98:101], v[196:199], v[212:215], v[98:101]
	v_mfma_f32_16x16x32_f16 v[86:89], v[188:191], v[220:223], v[86:89]
	v_mfma_f32_16x16x32_f16 v[82:85], v[196:199], v[220:223], v[82:85]
	v_mfma_f32_16x16x32_f16 v[70:73], v[188:191], v[240:243], v[70:73]
	v_mfma_f32_16x16x32_f16 v[66:69], v[196:199], v[240:243], v[66:69]
	s_barrier
	s_add_i32 s54, s54, s16
	v_lshl_add_u64 v[244:245], s[28:29], 0, v[132:133]
	s_mov_b32 m0, s54
	ds_read_b128 v[200:203], v182 offset:16384
	ds_read_b128 v[204:207], v182 offset:17408
	ds_read_b128 v[208:211], v182 offset:18432
	ds_read_b128 v[212:215], v182 offset:19456
	ds_read_b128 v[216:219], v182 offset:20480
	ds_read_b128 v[220:223], v182 offset:21504
	ds_read_b128 v[236:239], v182 offset:22528
	ds_read_b128 v[240:243], v182 offset:23552
	global_load_lds_dwordx4 v[244:245], off
	s_add_i32 m0, s54, 0x2000
	s_add_u32 s54, s28, 0x40000
	v_lshl_add_u64 v[246:247], s[28:29], 0, v[136:137]
	s_addc_u32 s55, s29, 0
	s_add_i32 s56, s56, s16
	global_load_lds_dwordx4 v[246:247], off
	v_lshl_add_u64 v[248:249], s[54:55], 0, v[132:133]
	s_mov_b32 m0, s56
	v_lshl_add_u64 v[250:251], s[30:31], 0, v[134:135]
	global_load_lds_dwordx4 v[248:249], off
	v_lshl_add_u64 v[248:249], s[54:55], 0, v[136:137]
	s_add_i32 m0, s56, 0x2000
	s_nop 0
	global_load_lds_dwordx4 v[248:249], off
	v_lshl_add_u64 v[248:249], s[30:31], 0, v[130:131]
	s_mov_b32 m0, s93
	s_nop 0
	global_load_lds_dwordx4 v[248:249], off
	s_mov_b32 m0, s13
	s_nop 0
	global_load_lds_dwordx4 v[250:251], off
	s_waitcnt vmcnt(8)
	s_waitcnt lgkmcnt(0)
	s_barrier
; #define PG8_STAGE(bufoff, gbase, voff) do { _Pragma("unroll") for (int _i = 0; _i < 2; ++_i) \
;         __builtin_amdgcn_global_load_lds((const unsigned*)((const char*)(gbase) + (voff)[_i]), (PG8_LAS unsigned*)(lds + (bufoff) + ldsw + _i * 8192), 16, 0, 0); } while (0)
; #define PG8_LDA(dst, b, h) do { _Pragma("unroll") for (int m = 0; m < 4; ++m) _Pragma("unroll") for (int k = 0; k < 2; ++k) dst[m][k] = *(const PG8_LAS bf16x8*)(lds + PG8_SA(b, h) + aoff + m * 2048 + k * 1024); } while (0)
; #define PG8_LDB(dst, b, h) do { _Pragma("unroll") for (int n = 0; n < 2; ++n) _Pragma("unroll") for (int k = 0; k < 2; ++k) dst[n][k] = *(const PG8_LAS bf16x8*)(lds + PG8_SB(b, h) + boff + n * 2048 + k * 1024); } while (0)
; #define PG8_WAIT_V(n) asm volatile("s_waitcnt vmcnt(" #n ")" ::: "memory")
; #define PG8_WAIT_L(n) asm volatile("s_waitcnt lgkmcnt(" #n ")" ::: "memory")
; #define PG8_BAR __builtin_amdgcn_s_barrier()
; #define PG8_SCHED __builtin_amdgcn_sched_barrier(0)
; template <class Epi, class Sched, bool ALIGN_EPI = false, bool SP2 = false>
; __device__ __forceinline__ void gemm_phase(PG8_LAS unsigned char* lds, const Gemm g, const Sched& S, const Epi& E) {
;     ...
;             PG8_WAIT_V(8); PG8_WAIT_L(0); PG8_BAR; PG8_MMA(1, 0, At, B0); PG8_MMA(1, 1, At, B1); PG8_BAR; PG8_SCHED;
;             PG8_LDB(B0, 1, 0); PG8_LDB(B1, 1, 1); PG8_SCHED; PG8_LDA(At, 1, 0); PG8_STAGE(PG8_SA(0, 1), a2 + hstep, voffA);
;             PG8_WAIT_V(8); PG8_WAIT_L(0); PG8_BAR; PG8_MMA(0, 0, At, B0); PG8_MMA(0, 1, At, B1); PG8_BAR; PG8_SCHED;
	s_waitcnt lgkmcnt(0)
	v_mfma_f32_16x16x32_f16 v[62:65], v[142:145], v[200:203], v[62:65]
	v_mfma_f32_16x16x32_f16 v[58:61], v[150:153], v[200:203], v[58:61]
	v_mfma_f32_16x16x32_f16 v[46:49], v[142:145], v[208:211], v[46:49]
	v_mfma_f32_16x16x32_f16 v[42:45], v[150:153], v[208:211], v[42:45]
	v_mfma_f32_16x16x32_f16 v[30:33], v[142:145], v[216:219], v[30:33]
	v_mfma_f32_16x16x32_f16 v[26:29], v[150:153], v[216:219], v[26:29]
	v_mfma_f32_16x16x32_f16 v[14:17], v[142:145], v[236:239], v[14:17]
	v_mfma_f32_16x16x32_f16 v[10:13], v[150:153], v[236:239], v[10:13]
	v_mfma_f32_16x16x32_f16 v[62:65], v[146:149], v[204:207], v[62:65]
	v_mfma_f32_16x16x32_f16 v[58:61], v[154:157], v[204:207], v[58:61]
	v_mfma_f32_16x16x32_f16 v[46:49], v[146:149], v[212:215], v[46:49]
	v_mfma_f32_16x16x32_f16 v[42:45], v[154:157], v[212:215], v[42:45]
	v_mfma_f32_16x16x32_f16 v[30:33], v[146:149], v[220:223], v[30:33]
	v_mfma_f32_16x16x32_f16 v[26:29], v[154:157], v[220:223], v[26:29]
	v_mfma_f32_16x16x32_f16 v[14:17], v[146:149], v[240:243], v[14:17]
	v_mfma_f32_16x16x32_f16 v[10:13], v[154:157], v[240:243], v[10:13]
	v_mfma_f32_16x16x32_f16 v[54:57], v[184:187], v[200:203], v[54:57]
	v_mfma_f32_16x16x32_f16 v[50:53], v[192:195], v[200:203], v[50:53]
	v_mfma_f32_16x16x32_f16 v[38:41], v[184:187], v[208:211], v[38:41]
	v_mfma_f32_16x16x32_f16 v[34:37], v[192:195], v[208:211], v[34:37]
	v_mfma_f32_16x16x32_f16 v[22:25], v[184:187], v[216:219], v[22:25]
	v_mfma_f32_16x16x32_f16 v[18:21], v[192:195], v[216:219], v[18:21]
	v_mfma_f32_16x16x32_f16 v[6:9], v[184:187], v[236:239], v[6:9]
	v_mfma_f32_16x16x32_f16 v[2:5], v[192:195], v[236:239], v[2:5]
	v_mfma_f32_16x16x32_f16 v[54:57], v[188:191], v[204:207], v[54:57]
	v_mfma_f32_16x16x32_f16 v[50:53], v[196:199], v[204:207], v[50:53]
	v_mfma_f32_16x16x32_f16 v[38:41], v[188:191], v[212:215], v[38:41]
	v_mfma_f32_16x16x32_f16 v[34:37], v[196:199], v[212:215], v[34:37]
	v_mfma_f32_16x16x32_f16 v[22:25], v[188:191], v[220:223], v[22:25]
	v_mfma_f32_16x16x32_f16 v[18:21], v[196:199], v[220:223], v[18:21]
	v_mfma_f32_16x16x32_f16 v[6:9], v[188:191], v[240:243], v[6:9]
	v_mfma_f32_16x16x32_f16 v[2:5], v[196:199], v[240:243], v[2:5]
	s_barrier
	s_add_i32 s54, 0, 0x18000
	v_add_u32_e32 v0, s54, v160
	s_add_i32 s55, 0, 0x1c000
	ds_read_b128 v[142:145], v0
	ds_read_b128 v[146:149], v0 offset:1024
	ds_read_b128 v[150:153], v0 offset:2048
	ds_read_b128 v[154:157], v0 offset:3072
	v_add_u32_e32 v0, s55, v160
	ds_read_b128 v[184:187], v0
	ds_read_b128 v[188:191], v0 offset:1024
	ds_read_b128 v[192:195], v0 offset:2048
	ds_read_b128 v[196:199], v0 offset:3072
	s_add_u32 s30, s30, 0x40000
	s_addc_u32 s31, s31, 0
	s_mov_b32 m0, s68
	v_lshl_add_u64 v[172:173], s[30:31], 0, v[130:131]
	ds_read_b128 v[200:203], v182 offset:32768
	ds_read_b128 v[204:207], v182 offset:33792
	ds_read_b128 v[208:211], v182 offset:34816
	ds_read_b128 v[212:215], v182 offset:35840
	ds_read_b128 v[216:219], v182 offset:36864
	ds_read_b128 v[220:223], v182 offset:37888
	ds_read_b128 v[236:239], v182 offset:38912
	ds_read_b128 v[240:243], v182 offset:39936
	global_load_lds_dwordx4 v[172:173], off
	v_lshl_add_u64 v[172:173], s[30:31], 0, v[134:135]
	s_mov_b32 m0, s72
	s_nop 0
	global_load_lds_dwordx4 v[172:173], off
	s_waitcnt vmcnt(8)
	s_waitcnt lgkmcnt(0)
	s_barrier
	s_waitcnt lgkmcnt(0)
	v_mfma_f32_16x16x32_f16 v[126:129], v[142:145], v[200:203], v[126:129]
	v_mfma_f32_16x16x32_f16 v[122:125], v[150:153], v[200:203], v[122:125]
	v_mfma_f32_16x16x32_f16 v[110:113], v[142:145], v[208:211], v[110:113]
	v_mfma_f32_16x16x32_f16 v[106:109], v[150:153], v[208:211], v[106:109]
	v_mfma_f32_16x16x32_f16 v[94:97], v[142:145], v[216:219], v[94:97]
	v_mfma_f32_16x16x32_f16 v[90:93], v[150:153], v[216:219], v[90:93]
	v_mfma_f32_16x16x32_f16 v[78:81], v[142:145], v[236:239], v[78:81]
	v_mfma_f32_16x16x32_f16 v[74:77], v[150:153], v[236:239], v[74:77]
	v_mfma_f32_16x16x32_f16 v[126:129], v[146:149], v[204:207], v[126:129]
	v_mfma_f32_16x16x32_f16 v[122:125], v[154:157], v[204:207], v[122:125]
	v_mfma_f32_16x16x32_f16 v[110:113], v[146:149], v[212:215], v[110:113]
	v_mfma_f32_16x16x32_f16 v[106:109], v[154:157], v[212:215], v[106:109]
	v_mfma_f32_16x16x32_f16 v[94:97], v[146:149], v[220:223], v[94:97]
	v_mfma_f32_16x16x32_f16 v[90:93], v[154:157], v[220:223], v[90:93]
	v_mfma_f32_16x16x32_f16 v[78:81], v[146:149], v[240:243], v[78:81]
	v_mfma_f32_16x16x32_f16 v[74:77], v[154:157], v[240:243], v[74:77]
	v_mfma_f32_16x16x32_f16 v[118:121], v[184:187], v[200:203], v[118:121]
	v_mfma_f32_16x16x32_f16 v[114:117], v[192:195], v[200:203], v[114:117]
	v_mfma_f32_16x16x32_f16 v[102:105], v[184:187], v[208:211], v[102:105]
	v_mfma_f32_16x16x32_f16 v[98:101], v[192:195], v[208:211], v[98:101]
	v_mfma_f32_16x16x32_f16 v[86:89], v[184:187], v[216:219], v[86:89]
	v_mfma_f32_16x16x32_f16 v[82:85], v[192:195], v[216:219], v[82:85]
	v_mfma_f32_16x16x32_f16 v[70:73], v[184:187], v[236:239], v[70:73]
	v_mfma_f32_16x16x32_f16 v[66:69], v[192:195], v[236:239], v[66:69]
	v_mfma_f32_16x16x32_f16 v[118:121], v[188:191], v[204:207], v[118:121]
	v_mfma_f32_16x16x32_f16 v[114:117], v[196:199], v[204:207], v[114:117]
	v_mfma_f32_16x16x32_f16 v[102:105], v[188:191], v[212:215], v[102:105]
	v_mfma_f32_16x16x32_f16 v[98:101], v[196:199], v[212:215], v[98:101]
	v_mfma_f32_16x16x32_f16 v[86:89], v[188:191], v[220:223], v[86:89]
	v_mfma_f32_16x16x32_f16 v[82:85], v[196:199], v[220:223], v[82:85]
	v_mfma_f32_16x16x32_f16 v[70:73], v[188:191], v[240:243], v[70:73]
	v_mfma_f32_16x16x32_f16 v[66:69], v[196:199], v[240:243], v[66:69]
	s_barrier
; #define PG8_STAGE(bufoff, gbase, voff) do { _Pragma("unroll") for (int _i = 0; _i < 2; ++_i) \
;         __builtin_amdgcn_global_load_lds((const unsigned*)((const char*)(gbase) + (voff)[_i]), (PG8_LAS unsigned*)(lds + (bufoff) + ldsw + _i * 8192), 16, 0, 0); } while (0)
; #define PG8_LDA(dst, b, h) do { _Pragma("unroll") for (int m = 0; m < 4; ++m) _Pragma("unroll") for (int k = 0; k < 2; ++k) dst[m][k] = *(const PG8_LAS bf16x8*)(lds + PG8_SA(b, h) + aoff + m * 2048 + k * 1024); } while (0)
; #define PG8_WAIT_V(n) asm volatile("s_waitcnt vmcnt(" #n ")" ::: "memory")
; #define PG8_WAIT_L(n) asm volatile("s_waitcnt lgkmcnt(" #n ")" ::: "memory")
; #define PG8_BAR __builtin_amdgcn_s_barrier()
; #define PG8_SCHED __builtin_amdgcn_sched_barrier(0)
; template <class Epi, class Sched, bool ALIGN_EPI = false, bool SP2 = false>
; __device__ __forceinline__ void gemm_phase(PG8_LAS unsigned char* lds, const Gemm g, const Sched& S, const Epi& E) {
;     ...
;             PG8_LDA(At, 1, 1); PG8_STAGE(PG8_SB(1, 0), b3, voffB); PG8_STAGE(PG8_SB(1, 1), b3 + hstep, voffB); PG8_STAGE(PG8_SA(1, 0), a3, voffA);
;             PG8_WAIT_V(8); PG8_WAIT_L(0); PG8_BAR; PG8_MMA(1, 0, At, B0); PG8_MMA(1, 1, At, B1); PG8_BAR; PG8_SCHED;
	s_add_i32 s30, s54, s16
	v_lshl_add_u64 v[172:173], v[244:245], 0, s[10:11]
	s_mov_b32 m0, s30
	ds_read_b128 v[200:203], v182 offset:49152
	ds_read_b128 v[204:207], v182 offset:50176
	ds_read_b128 v[208:211], v182 offset:51200
	ds_read_b128 v[212:215], v182 offset:52224
	ds_read_b128 v[216:219], v182 offset:53248
	ds_read_b128 v[220:223], v182 offset:54272
	ds_read_b128 v[236:239], v182 offset:55296
	ds_read_b128 v[240:243], v182 offset:56320
	global_load_lds_dwordx4 v[172:173], off
	s_add_i32 m0, s30, 0x2000
	s_add_u32 s28, s28, 0x40080
	v_lshl_add_u64 v[172:173], v[246:247], 0, s[10:11]
	s_addc_u32 s29, s29, 0
	s_add_i32 s30, s55, s16
	global_load_lds_dwordx4 v[172:173], off
	v_lshl_add_u64 v[172:173], s[28:29], 0, v[132:133]
	s_mov_b32 m0, s30
	s_nop 0
	global_load_lds_dwordx4 v[172:173], off
	v_lshl_add_u64 v[172:173], s[28:29], 0, v[136:137]
	s_add_i32 m0, s30, 0x2000
	s_nop 0
	global_load_lds_dwordx4 v[172:173], off
	v_lshl_add_u64 v[172:173], v[248:249], 0, s[10:11]
	s_mov_b32 m0, s36
	s_nop 0
	global_load_lds_dwordx4 v[172:173], off
	v_lshl_add_u64 v[172:173], v[250:251], 0, s[10:11]
	s_mov_b32 m0, s37
	s_nop 0
	global_load_lds_dwordx4 v[172:173], off
	s_waitcnt vmcnt(8)
	s_waitcnt lgkmcnt(0)
	s_barrier
	s_waitcnt lgkmcnt(0)
	v_mfma_f32_16x16x32_f16 v[62:65], v[142:145], v[200:203], v[62:65]
	v_mfma_f32_16x16x32_f16 v[58:61], v[150:153], v[200:203], v[58:61]
	v_mfma_f32_16x16x32_f16 v[46:49], v[142:145], v[208:211], v[46:49]
	v_mfma_f32_16x16x32_f16 v[42:45], v[150:153], v[208:211], v[42:45]
	v_mfma_f32_16x16x32_f16 v[30:33], v[142:145], v[216:219], v[30:33]
	v_mfma_f32_16x16x32_f16 v[26:29], v[150:153], v[216:219], v[26:29]
	v_mfma_f32_16x16x32_f16 v[14:17], v[142:145], v[236:239], v[14:17]
	v_mfma_f32_16x16x32_f16 v[10:13], v[150:153], v[236:239], v[10:13]
	v_mfma_f32_16x16x32_f16 v[62:65], v[146:149], v[204:207], v[62:65]
	v_mfma_f32_16x16x32_f16 v[58:61], v[154:157], v[204:207], v[58:61]
	v_mfma_f32_16x16x32_f16 v[46:49], v[146:149], v[212:215], v[46:49]
	v_mfma_f32_16x16x32_f16 v[42:45], v[154:157], v[212:215], v[42:45]
	v_mfma_f32_16x16x32_f16 v[30:33], v[146:149], v[220:223], v[30:33]
	v_mfma_f32_16x16x32_f16 v[26:29], v[154:157], v[220:223], v[26:29]
	v_mfma_f32_16x16x32_f16 v[14:17], v[146:149], v[240:243], v[14:17]
	v_mfma_f32_16x16x32_f16 v[10:13], v[154:157], v[240:243], v[10:13]
	v_mfma_f32_16x16x32_f16 v[54:57], v[184:187], v[200:203], v[54:57]
	v_mfma_f32_16x16x32_f16 v[50:53], v[192:195], v[200:203], v[50:53]
	v_mfma_f32_16x16x32_f16 v[38:41], v[184:187], v[208:211], v[38:41]
	v_mfma_f32_16x16x32_f16 v[34:37], v[192:195], v[208:211], v[34:37]
	v_mfma_f32_16x16x32_f16 v[22:25], v[184:187], v[216:219], v[22:25]
	v_mfma_f32_16x16x32_f16 v[18:21], v[192:195], v[216:219], v[18:21]
	v_mfma_f32_16x16x32_f16 v[6:9], v[184:187], v[236:239], v[6:9]
	v_mfma_f32_16x16x32_f16 v[2:5], v[192:195], v[236:239], v[2:5]
	v_mfma_f32_16x16x32_f16 v[54:57], v[188:191], v[204:207], v[54:57]
	v_mfma_f32_16x16x32_f16 v[50:53], v[196:199], v[204:207], v[50:53]
	v_mfma_f32_16x16x32_f16 v[38:41], v[188:191], v[212:215], v[38:41]
	v_mfma_f32_16x16x32_f16 v[34:37], v[196:199], v[212:215], v[34:37]
	v_mfma_f32_16x16x32_f16 v[22:25], v[188:191], v[220:223], v[22:25]
	v_mfma_f32_16x16x32_f16 v[18:21], v[196:199], v[220:223], v[18:21]
	v_mfma_f32_16x16x32_f16 v[6:9], v[188:191], v[240:243], v[6:9]
	v_mfma_f32_16x16x32_f16 v[2:5], v[196:199], v[240:243], v[2:5]
	s_barrier
	s_add_i32 s45, s45, 2
	s_add_u32 s26, s26, 0x100
	s_addc_u32 s27, s27, 0
	s_add_u32 s42, s42, 0x100
	s_addc_u32 s43, s43, 0
	s_cmp_gt_u32 s45, 13
	s_cbranch_scc0 .LBB0_153
	s_and_b64 vcc, exec, s[20:21]
	s_cbranch_vccz .LBB0_156
	s_barrier
